# mixer phase: drop loop-top vmcnt waits that only covered previous-iteration stores (GLA mma step, SGU item loop)
# speedup vs baseline: 1.0111x; 1.0111x over previous
; #define SGU_LOAD(ch) do { _Pragma("unroll") for (int i = 0; i < 4; ++i) pv[i] = *(const u32x4*)(Z + (size_t)((ch) * 128 + lrow + 32 * i) * ZW + ZSV + g * 128 + cs); } while (0)
; PHASE_FN void sgu_block(const Params& p, unsigned char* lds, int l, int g, int ch0, int nch) {
;     ...
;     int tid = threadIdx.x; asm volatile("" : "+v"(tid));
;     const int wid = __builtin_amdgcn_readfirstlane(tid >> 6), lane = tid & 63, lr = lane & 15, q4 = lane >> 4;
;     const bf16_t* __restrict__ Z = (const bf16_t*)(ws + WS_Z); bf16_t* __restrict__ MIX = (bf16_t*)(ws + WS_MIX);
;     const bf16_t* __restrict__ wsb = (const bf16_t*)(ws + WS_WSB) + (size_t)(l * 4 + g) * 128 * 128;
;     bf16_t* wl = (bf16_t*)(lds + L_SW);
;     const int lrow = tid >> 4, cs = (tid & 15) * 8;
; #pragma unroll
;     for (int i = 0; i < 4; ++i) *(u32x4*)(wl + (lrow + 32 * i) * SP + cs) = *(const u32x4*)(wsb + (size_t)(lrow + 32 * i) * 128 + cs);
;     const float* ngp = p.sgu_norm_g + (size_t)l * 512 + g * 128 + cs; const f32x4 g0 = *(const f32x4*)ngp, g1 = *(const f32x4*)(ngp + 4);
;     float bs[8];
; #pragma unroll
;     for (int pb = 0; pb < 8; ++pb) bs[pb] = p.b_s[(size_t)l * 512 + g * 128 + 16 * pb + lr];
;     const int ocol = g * 128 + 16 * wid + 4 * q4;
;     u32x4 pv[4];
;     ...
;     SGU_LOAD(ch0);
;     int buf = 0;
.LBB0_252:
	v_mov_b32_e32 v6, v206
	s_lshl_b32 s10, s9, 15
	s_add_i32 s10, s10, s4
	v_lshlrev_b32_e32 v0, 3, v6
	s_add_u32 s10, s91, s10
	v_readlane_b32 s11, v248, 34
	v_ashrrev_i32_e32 v24, 4, v6
	v_and_b32_e32 v40, 0x78, v0
	s_addc_u32 s11, s11, 0
	v_lshlrev_b32_e32 v152, 1, v40
	v_ashrrev_i32_e32 v25, 31, v24
	v_lshl_add_u64 v[0:1], s[10:11], 0, v[152:153]
	v_lshlrev_b64 v[2:3], 8, v[24:25]
	v_lshl_add_u64 v[4:5], v[0:1], 0, v[2:3]
	global_load_dwordx4 v[0:3], v[4:5], off
	s_movk_i32 s10, 0x110
	v_mul_lo_u32 v41, v24, s10
	v_add3_u32 v7, 0, v152, v41
	s_movk_i32 s10, 0x4000
	s_lshl_b32 s76, s9, 7
	v_and_b32_e32 v76, 15, v6
	v_lshlrev_b32_e32 v8, 2, v76
	v_readfirstlane_b32 s14, v6
	v_bfe_u32 v28, v6, 4, 2
	v_mov_b64_e32 v[20:21], s[60:61]
	v_and_b32_e32 v27, 64, v209
	v_xor_b32_e32 v25, 1, v209
	v_add_u32_e32 v27, 64, v27
	v_mul_u32_u24_e32 v89, 0x880, v28
	v_add_u32_e32 v90, s25, v24
	v_add_u32_e32 v91, s25, v76
	s_waitcnt vmcnt(0)
	ds_write_b128 v7, v[0:3]
	v_add_co_u32_e32 v0, vcc, s35, v4
	s_nop 1
	v_addc_co_u32_e32 v1, vcc, 0, v5, vcc
	global_load_dwordx4 v[0:3], v[0:1], off
	s_waitcnt vmcnt(0)
	ds_write_b128 v7, v[0:3] offset:8704
	v_add_co_u32_e32 v0, vcc, s10, v4
	s_movk_i32 s10, 0x6000
	s_nop 0
	v_addc_co_u32_e32 v1, vcc, 0, v5, vcc
	global_load_dwordx4 v[0:3], v[0:1], off
	s_waitcnt vmcnt(0)
	ds_write_b128 v7, v[0:3] offset:17408
	v_add_co_u32_e32 v0, vcc, s10, v4
	s_lshl_b64 s[10:11], s[76:77], 2
	s_nop 0
	v_addc_co_u32_e32 v1, vcc, 0, v5, vcc
	global_load_dwordx4 v[0:3], v[0:1], off
	s_add_u32 s12, s5, s10
	s_addc_u32 s13, s6, s11
	s_add_u32 s10, s7, s10
	v_lshlrev_b32_e32 v4, 2, v40
	s_addc_u32 s11, s8, s11
	s_waitcnt vmcnt(0)
	ds_write_b128 v7, v[0:3] offset:26112
	global_load_dwordx4 v[0:3], v4, s[12:13]
	s_nop 0
	global_load_dwordx4 v[4:7], v4, s[12:13] offset:16
	s_nop 0
	global_load_dword v77, v8, s[10:11]
	global_load_dword v78, v8, s[10:11] offset:64
	global_load_dword v79, v8, s[10:11] offset:128
	global_load_dword v80, v8, s[10:11] offset:192
	global_load_dword v81, v8, s[10:11] offset:256
	global_load_dword v82, v8, s[10:11] offset:320
	global_load_dword v83, v8, s[10:11] offset:384
	global_load_dword v84, v8, s[10:11] offset:448
	v_readlane_b32 s11, v247, 35
	s_ashr_i32 s10, s14, 2
	s_and_b32 s10, s10, -16
	v_add_u32_e32 v22, s11, v24
	v_mad_i64_i32 v[8:9], s[12:13], v22, s1, v[20:21]
	s_lshl_b32 s12, s9, 8
	s_mov_b32 s13, s77
	v_lshl_add_u64 v[8:9], v[8:9], 0, s[12:13]
	v_add_u32_e32 v12, 32, v22
	v_lshl_add_u64 v[8:9], v[8:9], 0, v[152:153]
	s_movk_i32 s11, 0x1000
	v_mad_i64_i32 v[12:13], s[14:15], v12, s1, v[20:21]
	v_add_co_u32_e32 v8, vcc, s11, v8
	v_lshl_add_u64 v[12:13], v[12:13], 0, s[12:13]
	v_add_u32_e32 v16, 64, v22
	v_addc_co_u32_e32 v9, vcc, 0, v9, vcc
	v_lshl_add_u64 v[12:13], v[12:13], 0, v[152:153]
	v_mad_i64_i32 v[16:17], s[14:15], v16, s1, v[20:21]
	v_add_co_u32_e32 v12, vcc, s11, v12
	v_lshl_add_u64 v[16:17], v[16:17], 0, s[12:13]
	v_add_u32_e32 v22, 0x60, v22
	v_addc_co_u32_e32 v13, vcc, 0, v13, vcc
	v_lshl_add_u64 v[16:17], v[16:17], 0, v[152:153]
	v_mad_i64_i32 v[20:21], s[14:15], v22, s1, v[20:21]
	v_add_co_u32_e32 v16, vcc, s11, v16
	v_lshl_add_u64 v[20:21], v[20:21], 0, s[12:13]
	s_nop 0
	v_addc_co_u32_e32 v17, vcc, 0, v17, vcc
	v_lshl_add_u64 v[20:21], v[20:21], 0, v[152:153]
	v_add_co_u32_e32 v20, vcc, s11, v20
	global_load_dwordx4 v[8:11], v[8:9], off offset:512
	s_nop 0
	v_addc_co_u32_e32 v21, vcc, 0, v21, vcc
	global_load_dwordx4 v[12:15], v[12:13], off offset:512
	v_cmp_lt_i32_e32 vcc, v25, v27
	global_load_dwordx4 v[16:19], v[16:17], off offset:512
	s_add_i32 s11, s10, s76
	global_load_dwordx4 v[20:23], v[20:21], off offset:512
	v_cndmask_b32_e32 v25, v209, v25, vcc
	v_lshlrev_b32_e32 v85, 2, v25
	v_xor_b32_e32 v25, 2, v209
	v_cmp_lt_i32_e32 vcc, v25, v27
	v_lshl_or_b32 v26, v28, 2, s11
	s_lshl_b32 s76, s76, 1
	v_cndmask_b32_e32 v25, v209, v25, vcc
	v_lshlrev_b32_e32 v86, 2, v25
	v_xor_b32_e32 v25, 4, v209
	v_cmp_lt_i32_e32 vcc, v25, v27
	v_readlane_b32 s11, v246, 37
	s_mov_b32 s12, 0
	v_cndmask_b32_e32 v25, v209, v25, vcc
	v_lshlrev_b32_e32 v87, 2, v25
	v_xor_b32_e32 v25, 8, v209
	v_cmp_lt_i32_e32 vcc, v25, v27
	v_ashrrev_i32_e32 v27, 31, v26
	v_lshl_add_u64 v[42:43], v[26:27], 1, s[60:61]
	v_cndmask_b32_e32 v25, v209, v25, vcc
	v_lshlrev_b32_e32 v88, 2, v25
	v_lshl_add_u32 v25, v28, 4, 0
	v_mul_u32_u24_e32 v28, 0x110, v76
	v_add_u32_e32 v92, v25, v28
	v_lshlrev_b64 v[44:45], 1, v[26:27]
	s_mov_b32 s13, 0
	s_waitcnt vmcnt(0)
	s_branch .LBB0_254

; __device__ __forceinline__ unsigned cvt_pk_bf16(float lo, float hi) { unsigned r; asm volatile("v_cvt_pk_bf16_f32 %0, %1, %2" : "=v"(r) : "v"(lo), "v"(hi)); return r; }
; __device__ __forceinline__ float bflo(unsigned w) { return __uint_as_float(w << 16); }
; __device__ __forceinline__ float bfhi(unsigned w) { return __uint_as_float(w & 0xffff0000u); }
; __device__ __forceinline__ f32x2 gelu_pk(f32x2 v) {
;     const f32x2 av = __builtin_elementwise_abs(v), d = av * 0.2316418882f + 1.0f;
;     f32x2 t; t.x = __builtin_amdgcn_rcpf(d.x); t.y = __builtin_amdgcn_rcpf(d.y);
;     f32x2 q = t * 0.5307027145f + (-0.7265760135f); q = q * t + 0.7107068705f; q = q * t + (-0.142248368f); q = q * t + 0.127414796f; q = q * t;
;     const f32x2 s = (v * v) * (-0.72134752044f);
;     f32x2 e; e.x = __builtin_amdgcn_exp2f(s.x); e.y = __builtin_amdgcn_exp2f(s.y);
;     const f32x2 m = v * (q * e), r = v - m;
;     f32x2 o; o.x = v.x < 0.f ? m.x : r.x; o.y = v.y < 0.f ? m.y : r.y; return o;
; }
; PHASE_FN void sgu_block(const Params& p, unsigned char* lds, int l, int g, int ch0, int nch) {
;     ...
;         bf16_t* vt = (bf16_t*)(lds + (buf ? L_SV1 : L_SV0));
; #pragma unroll
;         for (int i = 0; i < 4; ++i) { const u32x4 w = pv[i];
;             float v[8];
;             { const f32x2 a = gelu_pk((f32x2){bflo(w.x), bfhi(w.x)}), b2 = gelu_pk((f32x2){bflo(w.y), bfhi(w.y)}), c = gelu_pk((f32x2){bflo(w.z), bfhi(w.z)}), d = gelu_pk((f32x2){bflo(w.w), bfhi(w.w)});
;               v[0] = a.x; v[1] = a.y; v[2] = b2.x; v[3] = b2.y; v[4] = c.x; v[5] = c.y; v[6] = d.x; v[7] = d.y; }
;             float ss = 0.f;
; #pragma unroll
;             for (int k = 0; k < 8; ++k) ss += v[k] * v[k];
;             ss += __shfl_xor(ss, 1); ss += __shfl_xor(ss, 2); ss += __shfl_xor(ss, 4); ss += __shfl_xor(ss, 8);
;             const float rs = rsqrtf(ss * (1.0f / 128.0f) + EPS);
;             u32x4 o; o.x = cvt_pk_bf16(v[0] * rs * g0[0], v[1] * rs * g0[1]); o.y = cvt_pk_bf16(v[2] * rs * g0[2], v[3] * rs * g0[3]);
;             o.z = cvt_pk_bf16(v[4] * rs * g1[0], v[5] * rs * g1[1]); o.w = cvt_pk_bf16(v[6] * rs * g1[2], v[7] * rs * g1[3]);
;             *(u32x4*)(vt + (lrow + 32 * i) * SP + cs) = o; }
.LBB0_254:
	v_lshlrev_b32_e32 v26, 16, v8
	v_and_b32_e32 v27, 0xffff0000, v8
	v_and_b32_e32 v25, 0x7fffffff, v27
	v_and_b32_e32 v24, 0x7fffffff, v26
	v_pk_fma_f32 v[24:25], v[24:25], s[78:79], 1.0 op_sel_hi:[1,0,0]
	v_cmp_gt_f32_e32 vcc, 0, v26
	v_rcp_f32_e32 v28, v24
	v_rcp_f32_e32 v29, v25
	v_mov_b64_e32 v[24:25], s[66:67]
	s_cmp_eq_u32 s13, 0
	s_mov_b32 s14, 0x8800
	v_pk_fma_f32 v[30:31], v[28:29], s[74:75], v[24:25] op_sel_hi:[1,0,0]
	s_cselect_b32 s14, s14, 0x11000
	v_pk_fma_f32 v[30:31], v[28:29], v[30:31], s[62:63] op_sel_hi:[1,1,0]
	s_add_i32 s24, s14, 0
	v_pk_fma_f32 v[30:31], v[28:29], v[30:31], s[0:1] op_sel_hi:[1,1,0]
	v_lshlrev_b32_e32 v152, 1, v40
	v_pk_fma_f32 v[30:31], v[28:29], v[30:31], s[90:91] op_sel_hi:[1,1,0]
	s_cmp_ge_u32 s11, s81
	v_pk_mul_f32 v[28:29], v[28:29], v[30:31]
	v_pk_mul_f32 v[30:31], v[26:27], v[26:27]
	s_nop 0
	v_pk_mul_f32 v[30:31], v[30:31], s[68:69] op_sel_hi:[1,0]
	s_nop 0
	v_exp_f32_e32 v30, v30
	v_exp_f32_e32 v31, v31
	s_nop 0
	v_pk_mul_f32 v[28:29], v[30:31], v[28:29]
	s_nop 0
	v_pk_mul_f32 v[30:31], v[26:27], v[28:29]
	v_pk_fma_f32 v[28:29], v[26:27], v[28:29], v[26:27] neg_lo:[1,0,0] neg_hi:[1,0,0]
	v_lshlrev_b32_e32 v26, 16, v9
	v_cndmask_b32_e32 v36, v28, v30, vcc
	v_cmp_gt_f32_e32 vcc, 0, v27
	v_and_b32_e32 v27, 0xffff0000, v9
	v_and_b32_e32 v28, 0x7fffffff, v26
	v_cndmask_b32_e32 v37, v29, v31, vcc
	v_and_b32_e32 v29, 0x7fffffff, v27
	v_pk_fma_f32 v[28:29], v[28:29], s[78:79], 1.0 op_sel_hi:[1,0,0]
	v_cmp_gt_f32_e32 vcc, 0, v27
	v_rcp_f32_e32 v28, v28
	v_rcp_f32_e32 v29, v29
	v_cmp_gt_f32_e64 s[40:41], 0, v26
	v_mul_f32_e32 v32, v37, v37
	v_fmac_f32_e32 v32, v36, v36
	v_pk_fma_f32 v[30:31], v[28:29], s[74:75], v[24:25] op_sel_hi:[1,0,0]
	s_nop 0
	v_pk_fma_f32 v[30:31], v[28:29], v[30:31], s[62:63] op_sel_hi:[1,1,0]
	s_nop 0
	v_pk_fma_f32 v[30:31], v[28:29], v[30:31], s[0:1] op_sel_hi:[1,1,0]
	s_nop 0
	v_pk_fma_f32 v[30:31], v[28:29], v[30:31], s[90:91] op_sel_hi:[1,1,0]
	s_nop 0
	v_pk_mul_f32 v[28:29], v[28:29], v[30:31]
	v_pk_mul_f32 v[30:31], v[26:27], v[26:27]
	s_nop 0
	v_pk_mul_f32 v[30:31], v[30:31], s[68:69] op_sel_hi:[1,0]
	s_nop 0
	v_exp_f32_e32 v30, v30
	v_exp_f32_e32 v31, v31
	s_nop 0
	v_pk_mul_f32 v[28:29], v[30:31], v[28:29]
	s_nop 0
	v_pk_mul_f32 v[30:31], v[28:29], v[26:27]
	v_pk_fma_f32 v[28:29], v[28:29], v[26:27], v[26:27] neg_lo:[1,0,0] neg_hi:[1,0,0]
	s_nop 0
	v_cndmask_b32_e32 v27, v29, v31, vcc
	v_cndmask_b32_e64 v26, v28, v30, s[40:41]
	v_pk_mul_f32 v[28:29], v[26:27], v[26:27]
	s_nop 0
	v_add_f32_e32 v28, v28, v32
	v_add_f32_e32 v34, v29, v28
	v_and_b32_e32 v29, 0xffff0000, v10
	v_lshlrev_b32_e32 v28, 16, v10
	v_and_b32_e32 v31, 0x7fffffff, v29
	v_and_b32_e32 v30, 0x7fffffff, v28
	v_pk_fma_f32 v[30:31], v[30:31], s[78:79], 1.0 op_sel_hi:[1,0,0]
	v_cmp_gt_f32_e32 vcc, 0, v29
	v_rcp_f32_e32 v30, v30
	v_rcp_f32_e32 v31, v31
	v_cmp_gt_f32_e64 s[40:41], 0, v28
	v_pk_fma_f32 v[32:33], v[30:31], s[74:75], v[24:25] op_sel_hi:[1,0,0]
	s_nop 0
	v_pk_fma_f32 v[32:33], v[30:31], v[32:33], s[62:63] op_sel_hi:[1,1,0]
	s_nop 0
	v_pk_fma_f32 v[32:33], v[30:31], v[32:33], s[0:1] op_sel_hi:[1,1,0]
	s_nop 0
	v_pk_fma_f32 v[32:33], v[30:31], v[32:33], s[90:91] op_sel_hi:[1,1,0]
	s_nop 0
	v_pk_mul_f32 v[30:31], v[30:31], v[32:33]
	v_pk_mul_f32 v[32:33], v[28:29], v[28:29]
	s_nop 0
	v_pk_mul_f32 v[32:33], v[32:33], s[68:69] op_sel_hi:[1,0]
	s_nop 0
	v_exp_f32_e32 v32, v32
	v_exp_f32_e32 v33, v33
	s_nop 0
	v_pk_mul_f32 v[30:31], v[32:33], v[30:31]
	s_nop 0
	v_pk_mul_f32 v[32:33], v[30:31], v[28:29]
	v_pk_fma_f32 v[30:31], v[30:31], v[28:29], v[28:29] neg_lo:[1,0,0] neg_hi:[1,0,0]
	s_nop 0
	v_cndmask_b32_e32 v29, v31, v33, vcc
	v_cndmask_b32_e64 v28, v30, v32, s[40:41]
	v_pk_mul_f32 v[30:31], v[28:29], v[28:29]
	s_nop 0
	v_add_f32_e32 v30, v30, v34
	v_add_f32_e32 v38, v31, v30
	v_and_b32_e32 v31, 0xffff0000, v11
	v_lshlrev_b32_e32 v30, 16, v11
	v_and_b32_e32 v33, 0x7fffffff, v31
	v_and_b32_e32 v32, 0x7fffffff, v30
	v_pk_fma_f32 v[32:33], v[32:33], s[78:79], 1.0 op_sel_hi:[1,0,0]
	v_cmp_gt_f32_e32 vcc, 0, v31
	v_rcp_f32_e32 v32, v32
	v_rcp_f32_e32 v33, v33
	v_cmp_gt_f32_e64 s[40:41], 0, v30
	v_pk_fma_f32 v[34:35], v[32:33], s[74:75], v[24:25] op_sel_hi:[1,0,0]
	s_nop 0
	v_pk_fma_f32 v[34:35], v[32:33], v[34:35], s[62:63] op_sel_hi:[1,1,0]
	s_nop 0
	v_pk_fma_f32 v[34:35], v[32:33], v[34:35], s[0:1] op_sel_hi:[1,1,0]
	s_nop 0
	v_pk_fma_f32 v[34:35], v[32:33], v[34:35], s[90:91] op_sel_hi:[1,1,0]
	s_nop 0
	v_pk_mul_f32 v[32:33], v[32:33], v[34:35]
	v_pk_mul_f32 v[34:35], v[30:31], v[30:31]
	s_nop 0
	v_pk_mul_f32 v[34:35], v[34:35], s[68:69] op_sel_hi:[1,0]
	s_nop 0
	v_exp_f32_e32 v34, v34
	v_exp_f32_e32 v35, v35
	s_nop 0
	v_pk_mul_f32 v[32:33], v[34:35], v[32:33]
	s_nop 0
	v_pk_mul_f32 v[34:35], v[32:33], v[30:31]
	v_pk_fma_f32 v[32:33], v[32:33], v[30:31], v[30:31] neg_lo:[1,0,0] neg_hi:[1,0,0]
	s_nop 0
	v_cndmask_b32_e32 v35, v33, v35, vcc
	v_cndmask_b32_e64 v34, v32, v34, s[40:41]
	v_pk_mul_f32 v[30:31], v[34:35], v[34:35]
	s_nop 0
	v_add_f32_e32 v30, v30, v38
	v_add_f32_e32 v30, v31, v30
	ds_bpermute_b32 v31, v85, v30
	s_waitcnt lgkmcnt(0)
	v_add_f32_e32 v30, v30, v31
	ds_bpermute_b32 v31, v86, v30
	s_waitcnt lgkmcnt(0)
	v_add_f32_e32 v30, v30, v31
	ds_bpermute_b32 v31, v87, v30
	s_waitcnt lgkmcnt(0)
	v_add_f32_e32 v30, v30, v31
	ds_bpermute_b32 v31, v88, v30
	s_waitcnt lgkmcnt(0)
; __device__ __forceinline__ unsigned cvt_pk_bf16(float lo, float hi) { unsigned r; asm volatile("v_cvt_pk_bf16_f32 %0, %1, %2" : "=v"(r) : "v"(lo), "v"(hi)); return r; }
; __device__ __forceinline__ float bflo(unsigned w) { return __uint_as_float(w << 16); }
; __device__ __forceinline__ float bfhi(unsigned w) { return __uint_as_float(w & 0xffff0000u); }
; PHASE_FN void sgu_block(const Params& p, unsigned char* lds, int l, int g, int ch0, int nch) {
;     ...
;         for (int i = 0; i < 4; ++i) { const u32x4 w = pv[i];
;             float v[8];
;             { const f32x2 a = gelu_pk((f32x2){bflo(w.x), bfhi(w.x)}), b2 = gelu_pk((f32x2){bflo(w.y), bfhi(w.y)}), c = gelu_pk((f32x2){bflo(w.z), bfhi(w.z)}), d = gelu_pk((f32x2){bflo(w.w), bfhi(w.w)});
;               v[0] = a.x; v[1] = a.y; v[2] = b2.x; v[3] = b2.y; v[4] = c.x; v[5] = c.y; v[6] = d.x; v[7] = d.y; }
;             float ss = 0.f;
; #pragma unroll
;             for (int k = 0; k < 8; ++k) ss += v[k] * v[k];
;             ss += __shfl_xor(ss, 1); ss += __shfl_xor(ss, 2); ss += __shfl_xor(ss, 4); ss += __shfl_xor(ss, 8);
;             const float rs = rsqrtf(ss * (1.0f / 128.0f) + EPS);
;             u32x4 o; o.x = cvt_pk_bf16(v[0] * rs * g0[0], v[1] * rs * g0[1]); o.y = cvt_pk_bf16(v[2] * rs * g0[2], v[3] * rs * g0[3]);
;             o.z = cvt_pk_bf16(v[4] * rs * g1[0], v[5] * rs * g1[1]); o.w = cvt_pk_bf16(v[6] * rs * g1[2], v[7] * rs * g1[3]);
;             *(u32x4*)(vt + (lrow + 32 * i) * SP + cs) = o; }
	v_add_f32_e32 v30, v30, v31
	v_fmamk_f32 v30, v30, 0x3c000000, v208
	v_cmp_gt_f32_e32 vcc, s75, v30
	v_mul_f32_e32 v31, 0x4b800000, v30
	s_nop 0
	v_cndmask_b32_e32 v30, v30, v31, vcc
	v_rsq_f32_e32 v30, v30
	s_nop 0
	v_mul_f32_e32 v31, 0x45800000, v30
	v_cndmask_b32_e32 v33, v30, v31, vcc
	v_mul_f32_e32 v30, v36, v33
	v_mul_f32_e32 v31, v37, v33
	v_mul_f32_e32 v26, v26, v33
	v_mul_f32_e32 v27, v27, v33
	v_mul_f32_e32 v30, v0, v30
	v_mul_f32_e32 v31, v1, v31
	v_mul_f32_e32 v26, v2, v26
	v_mul_f32_e32 v27, v3, v27
	v_cvt_pk_bf16_f32 v30, v30, v31
	v_cvt_pk_bf16_f32 v31, v26, v27
	v_mul_f32_e32 v26, v28, v33
	v_mul_f32_e32 v27, v29, v33
	v_mul_f32_e32 v26, v4, v26
	v_mul_f32_e32 v27, v5, v27
	v_cvt_pk_bf16_f32 v32, v26, v27
	v_mul_f32_e32 v26, v34, v33
	v_mul_f32_e32 v27, v35, v33
	v_mul_f32_e32 v26, v6, v26
	v_mul_f32_e32 v27, v7, v27
	v_cvt_pk_bf16_f32 v33, v26, v27
	v_add3_u32 v28, s24, v152, v41
	v_lshlrev_b32_e32 v26, 16, v12
	v_and_b32_e32 v27, 0xffff0000, v12
	ds_write_b128 v28, v[30:33]
	v_and_b32_e32 v31, 0x7fffffff, v27
	v_and_b32_e32 v30, 0x7fffffff, v26
	v_pk_fma_f32 v[30:31], v[30:31], s[78:79], 1.0 op_sel_hi:[1,0,0]
	v_cmp_gt_f32_e32 vcc, 0, v26
	v_rcp_f32_e32 v30, v30
	v_rcp_f32_e32 v31, v31
	s_nop 0
	v_pk_fma_f32 v[32:33], v[30:31], s[74:75], v[24:25] op_sel_hi:[1,0,0]
	s_nop 0
	v_pk_fma_f32 v[32:33], v[30:31], v[32:33], s[62:63] op_sel_hi:[1,1,0]
	s_nop 0
	v_pk_fma_f32 v[32:33], v[30:31], v[32:33], s[0:1] op_sel_hi:[1,1,0]
	s_nop 0
	v_pk_fma_f32 v[32:33], v[30:31], v[32:33], s[90:91] op_sel_hi:[1,1,0]
	s_nop 0
	v_pk_mul_f32 v[30:31], v[30:31], v[32:33]
	v_pk_mul_f32 v[32:33], v[26:27], v[26:27]
	s_nop 0
	v_pk_mul_f32 v[32:33], v[32:33], s[68:69] op_sel_hi:[1,0]
	s_nop 0
	v_exp_f32_e32 v32, v32
	v_exp_f32_e32 v33, v33
	s_nop 0
	v_pk_mul_f32 v[30:31], v[32:33], v[30:31]
	s_nop 0
	v_pk_mul_f32 v[32:33], v[26:27], v[30:31]
	v_pk_fma_f32 v[30:31], v[26:27], v[30:31], v[26:27] neg_lo:[1,0,0] neg_hi:[1,0,0]
	v_lshlrev_b32_e32 v26, 16, v13
	v_cndmask_b32_e32 v29, v30, v32, vcc
	v_cmp_gt_f32_e32 vcc, 0, v27
	v_and_b32_e32 v27, 0xffff0000, v13
	v_and_b32_e32 v30, 0x7fffffff, v26
	v_cndmask_b32_e32 v38, v31, v33, vcc
	v_and_b32_e32 v31, 0x7fffffff, v27
	v_pk_fma_f32 v[30:31], v[30:31], s[78:79], 1.0 op_sel_hi:[1,0,0]
	v_cmp_gt_f32_e32 vcc, 0, v27
	v_rcp_f32_e32 v30, v30
	v_rcp_f32_e32 v31, v31
	v_cmp_gt_f32_e64 s[40:41], 0, v26
	v_mul_f32_e32 v34, v38, v38
	v_fmac_f32_e32 v34, v29, v29
	v_pk_fma_f32 v[32:33], v[30:31], s[74:75], v[24:25] op_sel_hi:[1,0,0]
	s_nop 0
	v_pk_fma_f32 v[32:33], v[30:31], v[32:33], s[62:63] op_sel_hi:[1,1,0]
	s_nop 0
	v_pk_fma_f32 v[32:33], v[30:31], v[32:33], s[0:1] op_sel_hi:[1,1,0]
	s_nop 0
	v_pk_fma_f32 v[32:33], v[30:31], v[32:33], s[90:91] op_sel_hi:[1,1,0]
	s_nop 0
	v_pk_mul_f32 v[30:31], v[30:31], v[32:33]
	v_pk_mul_f32 v[32:33], v[26:27], v[26:27]
	s_nop 0
	v_pk_mul_f32 v[32:33], v[32:33], s[68:69] op_sel_hi:[1,0]
	s_nop 0
	v_exp_f32_e32 v32, v32
	v_exp_f32_e32 v33, v33
	s_nop 0
	v_pk_mul_f32 v[30:31], v[32:33], v[30:31]
	s_nop 0
	v_pk_mul_f32 v[32:33], v[30:31], v[26:27]
	v_pk_fma_f32 v[30:31], v[30:31], v[26:27], v[26:27] neg_lo:[1,0,0] neg_hi:[1,0,0]
	s_nop 0
	v_cndmask_b32_e32 v27, v31, v33, vcc
	v_cndmask_b32_e64 v26, v30, v32, s[40:41]
	v_pk_mul_f32 v[30:31], v[26:27], v[26:27]
	s_nop 0
	v_add_f32_e32 v30, v30, v34
	v_add_f32_e32 v36, v31, v30
	v_and_b32_e32 v31, 0xffff0000, v14
	v_lshlrev_b32_e32 v30, 16, v14
	v_and_b32_e32 v33, 0x7fffffff, v31
	v_and_b32_e32 v32, 0x7fffffff, v30
	v_pk_fma_f32 v[32:33], v[32:33], s[78:79], 1.0 op_sel_hi:[1,0,0]
	v_cmp_gt_f32_e32 vcc, 0, v31
	v_rcp_f32_e32 v32, v32
	v_rcp_f32_e32 v33, v33
	v_cmp_gt_f32_e64 s[40:41], 0, v30
	v_pk_fma_f32 v[34:35], v[32:33], s[74:75], v[24:25] op_sel_hi:[1,0,0]
	s_nop 0
	v_pk_fma_f32 v[34:35], v[32:33], v[34:35], s[62:63] op_sel_hi:[1,1,0]
	s_nop 0
	v_pk_fma_f32 v[34:35], v[32:33], v[34:35], s[0:1] op_sel_hi:[1,1,0]
	s_nop 0
	v_pk_fma_f32 v[34:35], v[32:33], v[34:35], s[90:91] op_sel_hi:[1,1,0]
	s_nop 0
	v_pk_mul_f32 v[32:33], v[32:33], v[34:35]
	v_pk_mul_f32 v[34:35], v[30:31], v[30:31]
	s_nop 0
	v_pk_mul_f32 v[34:35], v[34:35], s[68:69] op_sel_hi:[1,0]
	s_nop 0
	v_exp_f32_e32 v34, v34
	v_exp_f32_e32 v35, v35
	s_nop 0
	v_pk_mul_f32 v[32:33], v[34:35], v[32:33]
	s_nop 0
	v_pk_mul_f32 v[34:35], v[32:33], v[30:31]
	v_pk_fma_f32 v[32:33], v[32:33], v[30:31], v[30:31] neg_lo:[1,0,0] neg_hi:[1,0,0]
	s_nop 0
	v_cndmask_b32_e32 v33, v33, v35, vcc
	v_cndmask_b32_e64 v32, v32, v34, s[40:41]
	v_pk_mul_f32 v[30:31], v[32:33], v[32:33]
	s_nop 0
	v_add_f32_e32 v30, v30, v36
	v_add_f32_e32 v39, v31, v30
	v_and_b32_e32 v31, 0xffff0000, v15
	v_lshlrev_b32_e32 v30, 16, v15
	v_and_b32_e32 v35, 0x7fffffff, v31
	v_and_b32_e32 v34, 0x7fffffff, v30
	v_pk_fma_f32 v[34:35], v[34:35], s[78:79], 1.0 op_sel_hi:[1,0,0]
	v_cmp_gt_f32_e32 vcc, 0, v31
	v_rcp_f32_e32 v34, v34
	v_rcp_f32_e32 v35, v35
	v_cmp_gt_f32_e64 s[40:41], 0, v30
	v_pk_fma_f32 v[36:37], v[34:35], s[74:75], v[24:25] op_sel_hi:[1,0,0]
	s_nop 0
	v_pk_fma_f32 v[36:37], v[34:35], v[36:37], s[62:63] op_sel_hi:[1,1,0]
	s_nop 0
	v_pk_fma_f32 v[36:37], v[34:35], v[36:37], s[0:1] op_sel_hi:[1,1,0]
	s_nop 0
	v_pk_fma_f32 v[36:37], v[34:35], v[36:37], s[90:91] op_sel_hi:[1,1,0]
	s_nop 0
	v_pk_mul_f32 v[34:35], v[34:35], v[36:37]
	v_pk_mul_f32 v[36:37], v[30:31], v[30:31]
	s_nop 0
	v_pk_mul_f32 v[36:37], v[36:37], s[68:69] op_sel_hi:[1,0]
	s_nop 0
	v_exp_f32_e32 v36, v36
	v_exp_f32_e32 v37, v37
	s_nop 0
	v_pk_mul_f32 v[34:35], v[36:37], v[34:35]
	s_nop 0
	v_pk_mul_f32 v[36:37], v[34:35], v[30:31]
	v_pk_fma_f32 v[34:35], v[34:35], v[30:31], v[30:31] neg_lo:[1,0,0] neg_hi:[1,0,0]
	s_nop 0
	v_cndmask_b32_e32 v35, v35, v37, vcc
	v_cndmask_b32_e64 v34, v34, v36, s[40:41]
	v_pk_mul_f32 v[30:31], v[34:35], v[34:35]
	s_nop 0
	v_add_f32_e32 v30, v30, v39
	v_add_f32_e32 v30, v31, v30
	ds_bpermute_b32 v31, v85, v30
	s_waitcnt lgkmcnt(0)
; __device__ __forceinline__ unsigned cvt_pk_bf16(float lo, float hi) { unsigned r; asm volatile("v_cvt_pk_bf16_f32 %0, %1, %2" : "=v"(r) : "v"(lo), "v"(hi)); return r; }
; __device__ __forceinline__ float bflo(unsigned w) { return __uint_as_float(w << 16); }
; __device__ __forceinline__ float bfhi(unsigned w) { return __uint_as_float(w & 0xffff0000u); }
; PHASE_FN void sgu_block(const Params& p, unsigned char* lds, int l, int g, int ch0, int nch) {
;     ...
;         for (int i = 0; i < 4; ++i) { const u32x4 w = pv[i];
;             float v[8];
;             { const f32x2 a = gelu_pk((f32x2){bflo(w.x), bfhi(w.x)}), b2 = gelu_pk((f32x2){bflo(w.y), bfhi(w.y)}), c = gelu_pk((f32x2){bflo(w.z), bfhi(w.z)}), d = gelu_pk((f32x2){bflo(w.w), bfhi(w.w)});
;               v[0] = a.x; v[1] = a.y; v[2] = b2.x; v[3] = b2.y; v[4] = c.x; v[5] = c.y; v[6] = d.x; v[7] = d.y; }
;             float ss = 0.f;
; #pragma unroll
;             for (int k = 0; k < 8; ++k) ss += v[k] * v[k];
;             ss += __shfl_xor(ss, 1); ss += __shfl_xor(ss, 2); ss += __shfl_xor(ss, 4); ss += __shfl_xor(ss, 8);
;             const float rs = rsqrtf(ss * (1.0f / 128.0f) + EPS);
;             u32x4 o; o.x = cvt_pk_bf16(v[0] * rs * g0[0], v[1] * rs * g0[1]); o.y = cvt_pk_bf16(v[2] * rs * g0[2], v[3] * rs * g0[3]);
;             o.z = cvt_pk_bf16(v[4] * rs * g1[0], v[5] * rs * g1[1]); o.w = cvt_pk_bf16(v[6] * rs * g1[2], v[7] * rs * g1[3]);
;             *(u32x4*)(vt + (lrow + 32 * i) * SP + cs) = o; }
	v_add_f32_e32 v30, v30, v31
	ds_bpermute_b32 v31, v86, v30
	s_waitcnt lgkmcnt(0)
	v_add_f32_e32 v30, v30, v31
	ds_bpermute_b32 v31, v87, v30
	s_waitcnt lgkmcnt(0)
	v_add_f32_e32 v30, v30, v31
	ds_bpermute_b32 v31, v88, v30
	s_waitcnt lgkmcnt(0)
	v_add_f32_e32 v30, v30, v31
	v_fmamk_f32 v30, v30, 0x3c000000, v208
	v_cmp_gt_f32_e32 vcc, s75, v30
	v_mul_f32_e32 v31, 0x4b800000, v30
	s_nop 0
	v_cndmask_b32_e32 v30, v30, v31, vcc
	v_rsq_f32_e32 v30, v30
	s_nop 0
	v_mul_f32_e32 v31, 0x45800000, v30
	v_cndmask_b32_e32 v36, v30, v31, vcc
	v_mul_f32_e32 v30, v38, v36
	v_mul_f32_e32 v26, v26, v36
	v_mul_f32_e32 v27, v27, v36
	v_mul_f32_e32 v29, v29, v36
	v_mul_f32_e32 v30, v1, v30
	v_mul_f32_e32 v26, v2, v26
	v_mul_f32_e32 v27, v3, v27
	v_mul_f32_e32 v29, v0, v29
	v_cvt_pk_bf16_f32 v30, v29, v30
	v_cvt_pk_bf16_f32 v31, v26, v27
	v_mul_f32_e32 v26, v32, v36
	v_mul_f32_e32 v27, v33, v36
	v_mul_f32_e32 v26, v4, v26
	v_mul_f32_e32 v27, v5, v27
	v_cvt_pk_bf16_f32 v32, v26, v27
	v_mul_f32_e32 v26, v34, v36
	v_mul_f32_e32 v27, v35, v36
	v_mul_f32_e32 v26, v6, v26
	v_mul_f32_e32 v27, v7, v27
	v_cvt_pk_bf16_f32 v33, v26, v27
	v_lshlrev_b32_e32 v26, 16, v16
	v_and_b32_e32 v27, 0xffff0000, v16
	ds_write_b128 v28, v[30:33] offset:8704
	v_and_b32_e32 v31, 0x7fffffff, v27
	v_and_b32_e32 v30, 0x7fffffff, v26
	v_pk_fma_f32 v[30:31], v[30:31], s[78:79], 1.0 op_sel_hi:[1,0,0]
	v_cmp_gt_f32_e32 vcc, 0, v26
	v_rcp_f32_e32 v30, v30
	v_rcp_f32_e32 v31, v31
	s_nop 0
	v_pk_fma_f32 v[32:33], v[30:31], s[74:75], v[24:25] op_sel_hi:[1,0,0]
	s_nop 0
	v_pk_fma_f32 v[32:33], v[30:31], v[32:33], s[62:63] op_sel_hi:[1,1,0]
	s_nop 0
	v_pk_fma_f32 v[32:33], v[30:31], v[32:33], s[0:1] op_sel_hi:[1,1,0]
	s_nop 0
	v_pk_fma_f32 v[32:33], v[30:31], v[32:33], s[90:91] op_sel_hi:[1,1,0]
	s_nop 0
	v_pk_mul_f32 v[30:31], v[30:31], v[32:33]
	v_pk_mul_f32 v[32:33], v[26:27], v[26:27]
	s_nop 0
	v_pk_mul_f32 v[32:33], v[32:33], s[68:69] op_sel_hi:[1,0]
	s_nop 0
	v_exp_f32_e32 v32, v32
	v_exp_f32_e32 v33, v33
	s_nop 0
	v_pk_mul_f32 v[30:31], v[32:33], v[30:31]
	s_nop 0
	v_pk_mul_f32 v[32:33], v[26:27], v[30:31]
	v_pk_fma_f32 v[30:31], v[26:27], v[30:31], v[26:27] neg_lo:[1,0,0] neg_hi:[1,0,0]
	v_lshlrev_b32_e32 v26, 16, v17
	v_cndmask_b32_e32 v29, v30, v32, vcc
	v_cmp_gt_f32_e32 vcc, 0, v27
	v_and_b32_e32 v27, 0xffff0000, v17
	v_and_b32_e32 v30, 0x7fffffff, v26
	v_cndmask_b32_e32 v38, v31, v33, vcc
	v_and_b32_e32 v31, 0x7fffffff, v27
	v_pk_fma_f32 v[30:31], v[30:31], s[78:79], 1.0 op_sel_hi:[1,0,0]
	v_cmp_gt_f32_e32 vcc, 0, v27
	v_rcp_f32_e32 v30, v30
	v_rcp_f32_e32 v31, v31
	v_cmp_gt_f32_e64 s[40:41], 0, v26
	v_mul_f32_e32 v34, v38, v38
	v_fmac_f32_e32 v34, v29, v29
	v_pk_fma_f32 v[32:33], v[30:31], s[74:75], v[24:25] op_sel_hi:[1,0,0]
	s_nop 0
	v_pk_fma_f32 v[32:33], v[30:31], v[32:33], s[62:63] op_sel_hi:[1,1,0]
	s_nop 0
	v_pk_fma_f32 v[32:33], v[30:31], v[32:33], s[0:1] op_sel_hi:[1,1,0]
	s_nop 0
	v_pk_fma_f32 v[32:33], v[30:31], v[32:33], s[90:91] op_sel_hi:[1,1,0]
	s_nop 0
	v_pk_mul_f32 v[30:31], v[30:31], v[32:33]
	v_pk_mul_f32 v[32:33], v[26:27], v[26:27]
	s_nop 0
	v_pk_mul_f32 v[32:33], v[32:33], s[68:69] op_sel_hi:[1,0]
	s_nop 0
	v_exp_f32_e32 v32, v32
	v_exp_f32_e32 v33, v33
	s_nop 0
	v_pk_mul_f32 v[30:31], v[32:33], v[30:31]
	s_nop 0
	v_pk_mul_f32 v[32:33], v[30:31], v[26:27]
	v_pk_fma_f32 v[30:31], v[30:31], v[26:27], v[26:27] neg_lo:[1,0,0] neg_hi:[1,0,0]
	s_nop 0
	v_cndmask_b32_e32 v27, v31, v33, vcc
	v_cndmask_b32_e64 v26, v30, v32, s[40:41]
	v_pk_mul_f32 v[30:31], v[26:27], v[26:27]
	s_nop 0
	v_add_f32_e32 v30, v30, v34
	v_add_f32_e32 v36, v31, v30
	v_and_b32_e32 v31, 0xffff0000, v18
	v_lshlrev_b32_e32 v30, 16, v18
	v_and_b32_e32 v33, 0x7fffffff, v31
	v_and_b32_e32 v32, 0x7fffffff, v30
	v_pk_fma_f32 v[32:33], v[32:33], s[78:79], 1.0 op_sel_hi:[1,0,0]
	v_cmp_gt_f32_e32 vcc, 0, v31
	v_rcp_f32_e32 v32, v32
	v_rcp_f32_e32 v33, v33
	v_cmp_gt_f32_e64 s[40:41], 0, v30
	v_pk_fma_f32 v[34:35], v[32:33], s[74:75], v[24:25] op_sel_hi:[1,0,0]
	s_nop 0
	v_pk_fma_f32 v[34:35], v[32:33], v[34:35], s[62:63] op_sel_hi:[1,1,0]
	s_nop 0
	v_pk_fma_f32 v[34:35], v[32:33], v[34:35], s[0:1] op_sel_hi:[1,1,0]
	s_nop 0
	v_pk_fma_f32 v[34:35], v[32:33], v[34:35], s[90:91] op_sel_hi:[1,1,0]
	s_nop 0
	v_pk_mul_f32 v[32:33], v[32:33], v[34:35]
	v_pk_mul_f32 v[34:35], v[30:31], v[30:31]
	s_nop 0
	v_pk_mul_f32 v[34:35], v[34:35], s[68:69] op_sel_hi:[1,0]
	s_nop 0
	v_exp_f32_e32 v34, v34
	v_exp_f32_e32 v35, v35
	s_nop 0
	v_pk_mul_f32 v[32:33], v[34:35], v[32:33]
	s_nop 0
	v_pk_mul_f32 v[34:35], v[32:33], v[30:31]
	v_pk_fma_f32 v[32:33], v[32:33], v[30:31], v[30:31] neg_lo:[1,0,0] neg_hi:[1,0,0]
	s_nop 0
	v_cndmask_b32_e32 v33, v33, v35, vcc
	v_cndmask_b32_e64 v32, v32, v34, s[40:41]
	v_pk_mul_f32 v[30:31], v[32:33], v[32:33]
	s_nop 0
	v_add_f32_e32 v30, v30, v36
	v_add_f32_e32 v39, v31, v30
	v_and_b32_e32 v31, 0xffff0000, v19
	v_lshlrev_b32_e32 v30, 16, v19
	v_and_b32_e32 v35, 0x7fffffff, v31
	v_and_b32_e32 v34, 0x7fffffff, v30
	v_pk_fma_f32 v[34:35], v[34:35], s[78:79], 1.0 op_sel_hi:[1,0,0]
	v_cmp_gt_f32_e32 vcc, 0, v31
	v_rcp_f32_e32 v34, v34
	v_rcp_f32_e32 v35, v35
	v_cmp_gt_f32_e64 s[40:41], 0, v30
	v_pk_fma_f32 v[36:37], v[34:35], s[74:75], v[24:25] op_sel_hi:[1,0,0]
	s_nop 0
	v_pk_fma_f32 v[36:37], v[34:35], v[36:37], s[62:63] op_sel_hi:[1,1,0]
	s_nop 0
	v_pk_fma_f32 v[36:37], v[34:35], v[36:37], s[0:1] op_sel_hi:[1,1,0]
	s_nop 0
	v_pk_fma_f32 v[36:37], v[34:35], v[36:37], s[90:91] op_sel_hi:[1,1,0]
	s_nop 0
	v_pk_mul_f32 v[34:35], v[34:35], v[36:37]
	v_pk_mul_f32 v[36:37], v[30:31], v[30:31]
	s_nop 0
	v_pk_mul_f32 v[36:37], v[36:37], s[68:69] op_sel_hi:[1,0]
	s_nop 0
	v_exp_f32_e32 v36, v36
	v_exp_f32_e32 v37, v37
	s_nop 0
	v_pk_mul_f32 v[34:35], v[36:37], v[34:35]
	s_nop 0
	v_pk_mul_f32 v[36:37], v[34:35], v[30:31]
	v_pk_fma_f32 v[34:35], v[34:35], v[30:31], v[30:31] neg_lo:[1,0,0] neg_hi:[1,0,0]
	s_nop 0
	v_cndmask_b32_e32 v35, v35, v37, vcc
	v_cndmask_b32_e64 v34, v34, v36, s[40:41]
	v_pk_mul_f32 v[30:31], v[34:35], v[34:35]
	s_nop 0
	v_add_f32_e32 v30, v30, v39
	v_add_f32_e32 v30, v31, v30
	ds_bpermute_b32 v31, v85, v30
	s_waitcnt lgkmcnt(0)
; __device__ __forceinline__ unsigned cvt_pk_bf16(float lo, float hi) { unsigned r; asm volatile("v_cvt_pk_bf16_f32 %0, %1, %2" : "=v"(r) : "v"(lo), "v"(hi)); return r; }
; __device__ __forceinline__ float bflo(unsigned w) { return __uint_as_float(w << 16); }
; __device__ __forceinline__ float bfhi(unsigned w) { return __uint_as_float(w & 0xffff0000u); }
; PHASE_FN void sgu_block(const Params& p, unsigned char* lds, int l, int g, int ch0, int nch) {
;     ...
;         for (int i = 0; i < 4; ++i) { const u32x4 w = pv[i];
;             float v[8];
;             { const f32x2 a = gelu_pk((f32x2){bflo(w.x), bfhi(w.x)}), b2 = gelu_pk((f32x2){bflo(w.y), bfhi(w.y)}), c = gelu_pk((f32x2){bflo(w.z), bfhi(w.z)}), d = gelu_pk((f32x2){bflo(w.w), bfhi(w.w)});
;               v[0] = a.x; v[1] = a.y; v[2] = b2.x; v[3] = b2.y; v[4] = c.x; v[5] = c.y; v[6] = d.x; v[7] = d.y; }
;             float ss = 0.f;
; #pragma unroll
;             for (int k = 0; k < 8; ++k) ss += v[k] * v[k];
;             ss += __shfl_xor(ss, 1); ss += __shfl_xor(ss, 2); ss += __shfl_xor(ss, 4); ss += __shfl_xor(ss, 8);
;             const float rs = rsqrtf(ss * (1.0f / 128.0f) + EPS);
;             u32x4 o; o.x = cvt_pk_bf16(v[0] * rs * g0[0], v[1] * rs * g0[1]); o.y = cvt_pk_bf16(v[2] * rs * g0[2], v[3] * rs * g0[3]);
;             o.z = cvt_pk_bf16(v[4] * rs * g1[0], v[5] * rs * g1[1]); o.w = cvt_pk_bf16(v[6] * rs * g1[2], v[7] * rs * g1[3]);
;             *(u32x4*)(vt + (lrow + 32 * i) * SP + cs) = o; }
	v_add_f32_e32 v30, v30, v31
	ds_bpermute_b32 v31, v86, v30
	s_waitcnt lgkmcnt(0)
	v_add_f32_e32 v30, v30, v31
	ds_bpermute_b32 v31, v87, v30
	s_waitcnt lgkmcnt(0)
	v_add_f32_e32 v30, v30, v31
	ds_bpermute_b32 v31, v88, v30
	s_waitcnt lgkmcnt(0)
	v_add_f32_e32 v30, v30, v31
	v_fmamk_f32 v30, v30, 0x3c000000, v208
	v_cmp_gt_f32_e32 vcc, s75, v30
	v_mul_f32_e32 v31, 0x4b800000, v30
	s_nop 0
	v_cndmask_b32_e32 v30, v30, v31, vcc
	v_rsq_f32_e32 v30, v30
	s_nop 0
	v_mul_f32_e32 v31, 0x45800000, v30
	v_cndmask_b32_e32 v36, v30, v31, vcc
	v_mul_f32_e32 v30, v38, v36
	v_mul_f32_e32 v26, v26, v36
	v_mul_f32_e32 v27, v27, v36
	v_mul_f32_e32 v29, v29, v36
	v_mul_f32_e32 v30, v1, v30
	v_mul_f32_e32 v26, v2, v26
	v_mul_f32_e32 v27, v3, v27
	v_mul_f32_e32 v29, v0, v29
	v_cvt_pk_bf16_f32 v30, v29, v30
	v_cvt_pk_bf16_f32 v31, v26, v27
	v_mul_f32_e32 v26, v32, v36
	v_mul_f32_e32 v27, v33, v36
	v_mul_f32_e32 v26, v4, v26
	v_mul_f32_e32 v27, v5, v27
	v_cvt_pk_bf16_f32 v32, v26, v27
	v_mul_f32_e32 v26, v34, v36
	v_mul_f32_e32 v27, v35, v36
	v_mul_f32_e32 v26, v6, v26
	v_mul_f32_e32 v27, v7, v27
	v_cvt_pk_bf16_f32 v33, v26, v27
	v_lshlrev_b32_e32 v26, 16, v20
	v_and_b32_e32 v27, 0xffff0000, v20
	ds_write_b128 v28, v[30:33] offset:17408
	v_and_b32_e32 v31, 0x7fffffff, v27
	v_and_b32_e32 v30, 0x7fffffff, v26
	v_pk_fma_f32 v[30:31], v[30:31], s[78:79], 1.0 op_sel_hi:[1,0,0]
	v_cmp_gt_f32_e32 vcc, 0, v26
	v_rcp_f32_e32 v30, v30
	v_rcp_f32_e32 v31, v31
	s_nop 0
	v_pk_fma_f32 v[32:33], v[30:31], s[74:75], v[24:25] op_sel_hi:[1,0,0]
	s_nop 0
	v_pk_fma_f32 v[32:33], v[30:31], v[32:33], s[62:63] op_sel_hi:[1,1,0]
	s_nop 0
	v_pk_fma_f32 v[32:33], v[30:31], v[32:33], s[0:1] op_sel_hi:[1,1,0]
	s_nop 0
	v_pk_fma_f32 v[32:33], v[30:31], v[32:33], s[90:91] op_sel_hi:[1,1,0]
	s_nop 0
	v_pk_mul_f32 v[30:31], v[30:31], v[32:33]
	v_pk_mul_f32 v[32:33], v[26:27], v[26:27]
	s_nop 0
	v_pk_mul_f32 v[32:33], v[32:33], s[68:69] op_sel_hi:[1,0]
	s_nop 0
	v_exp_f32_e32 v32, v32
	v_exp_f32_e32 v33, v33
	s_nop 0
	v_pk_mul_f32 v[30:31], v[32:33], v[30:31]
	s_nop 0
	v_pk_mul_f32 v[32:33], v[26:27], v[30:31]
	v_pk_fma_f32 v[30:31], v[26:27], v[30:31], v[26:27] neg_lo:[1,0,0] neg_hi:[1,0,0]
	v_lshlrev_b32_e32 v26, 16, v21
	v_cndmask_b32_e32 v29, v30, v32, vcc
	v_cmp_gt_f32_e32 vcc, 0, v27
	v_and_b32_e32 v27, 0xffff0000, v21
	v_and_b32_e32 v30, 0x7fffffff, v26
	v_cndmask_b32_e32 v36, v31, v33, vcc
	v_and_b32_e32 v31, 0x7fffffff, v27
	v_pk_fma_f32 v[30:31], v[30:31], s[78:79], 1.0 op_sel_hi:[1,0,0]
	v_cmp_gt_f32_e32 vcc, 0, v27
	v_rcp_f32_e32 v30, v30
	v_rcp_f32_e32 v31, v31
	v_cmp_gt_f32_e64 s[40:41], 0, v26
	v_mul_f32_e32 v34, v36, v36
	v_fmac_f32_e32 v34, v29, v29
	v_pk_fma_f32 v[32:33], v[30:31], s[74:75], v[24:25] op_sel_hi:[1,0,0]
	s_nop 0
	v_pk_fma_f32 v[32:33], v[30:31], v[32:33], s[62:63] op_sel_hi:[1,1,0]
	s_nop 0
	v_pk_fma_f32 v[32:33], v[30:31], v[32:33], s[0:1] op_sel_hi:[1,1,0]
	s_nop 0
	v_pk_fma_f32 v[32:33], v[30:31], v[32:33], s[90:91] op_sel_hi:[1,1,0]
	s_nop 0
	v_pk_mul_f32 v[30:31], v[30:31], v[32:33]
	v_pk_mul_f32 v[32:33], v[26:27], v[26:27]
	s_nop 0
	v_pk_mul_f32 v[32:33], v[32:33], s[68:69] op_sel_hi:[1,0]
	s_nop 0
	v_exp_f32_e32 v32, v32
	v_exp_f32_e32 v33, v33
	s_nop 0
	v_pk_mul_f32 v[30:31], v[32:33], v[30:31]
	s_nop 0
	v_pk_mul_f32 v[32:33], v[30:31], v[26:27]
	v_pk_fma_f32 v[30:31], v[30:31], v[26:27], v[26:27] neg_lo:[1,0,0] neg_hi:[1,0,0]
	s_nop 0
	v_cndmask_b32_e32 v27, v31, v33, vcc
	v_cndmask_b32_e64 v26, v30, v32, s[40:41]
	v_pk_mul_f32 v[30:31], v[26:27], v[26:27]
	s_nop 0
	v_add_f32_e32 v30, v30, v34
	v_add_f32_e32 v37, v31, v30
	v_and_b32_e32 v31, 0xffff0000, v22
	v_lshlrev_b32_e32 v30, 16, v22
	v_and_b32_e32 v33, 0x7fffffff, v31
	v_and_b32_e32 v32, 0x7fffffff, v30
	v_pk_fma_f32 v[32:33], v[32:33], s[78:79], 1.0 op_sel_hi:[1,0,0]
	v_cmp_gt_f32_e32 vcc, 0, v31
	v_rcp_f32_e32 v32, v32
	v_rcp_f32_e32 v33, v33
	v_cmp_gt_f32_e64 s[40:41], 0, v30
	v_pk_fma_f32 v[34:35], v[32:33], s[74:75], v[24:25] op_sel_hi:[1,0,0]
	s_nop 0
	v_pk_fma_f32 v[34:35], v[32:33], v[34:35], s[62:63] op_sel_hi:[1,1,0]
	s_nop 0
	v_pk_fma_f32 v[34:35], v[32:33], v[34:35], s[0:1] op_sel_hi:[1,1,0]
	s_nop 0
	v_pk_fma_f32 v[34:35], v[32:33], v[34:35], s[90:91] op_sel_hi:[1,1,0]
	s_nop 0
	v_pk_mul_f32 v[32:33], v[32:33], v[34:35]
	v_pk_mul_f32 v[34:35], v[30:31], v[30:31]
	s_nop 0
	v_pk_mul_f32 v[34:35], v[34:35], s[68:69] op_sel_hi:[1,0]
	s_nop 0
	v_exp_f32_e32 v34, v34
	v_exp_f32_e32 v35, v35
	s_nop 0
	v_pk_mul_f32 v[32:33], v[34:35], v[32:33]
	s_nop 0
	v_pk_mul_f32 v[34:35], v[32:33], v[30:31]
	v_pk_fma_f32 v[32:33], v[32:33], v[30:31], v[30:31] neg_lo:[1,0,0] neg_hi:[1,0,0]
	s_nop 0
	v_cndmask_b32_e32 v31, v33, v35, vcc
	v_cndmask_b32_e64 v30, v32, v34, s[40:41]
	v_pk_mul_f32 v[32:33], v[30:31], v[30:31]
	s_nop 0
	v_add_f32_e32 v32, v32, v37
	v_add_f32_e32 v37, v33, v32
	v_and_b32_e32 v33, 0xffff0000, v23
	v_lshlrev_b32_e32 v32, 16, v23
	v_and_b32_e32 v35, 0x7fffffff, v33
	v_and_b32_e32 v34, 0x7fffffff, v32
	v_pk_fma_f32 v[34:35], v[34:35], s[78:79], 1.0 op_sel_hi:[1,0,0]
	v_cmp_gt_f32_e32 vcc, 0, v33
	v_rcp_f32_e32 v34, v34
	v_rcp_f32_e32 v35, v35
	v_cmp_gt_f32_e64 s[40:41], 0, v32
	v_pk_fma_f32 v[24:25], v[34:35], s[74:75], v[24:25] op_sel_hi:[1,0,0]
	s_nop 0
	v_pk_fma_f32 v[24:25], v[34:35], v[24:25], s[62:63] op_sel_hi:[1,1,0]
	s_nop 0
	v_pk_fma_f32 v[24:25], v[34:35], v[24:25], s[0:1] op_sel_hi:[1,1,0]
	s_nop 0
	v_pk_fma_f32 v[24:25], v[34:35], v[24:25], s[90:91] op_sel_hi:[1,1,0]
	s_nop 0
	v_pk_mul_f32 v[24:25], v[34:35], v[24:25]
	v_pk_mul_f32 v[34:35], v[32:33], v[32:33]
	s_nop 0
	v_pk_mul_f32 v[34:35], v[34:35], s[68:69] op_sel_hi:[1,0]
	s_nop 0
	v_exp_f32_e32 v34, v34
	v_exp_f32_e32 v35, v35
	s_nop 0
	v_pk_mul_f32 v[24:25], v[34:35], v[24:25]
	s_nop 0
	v_pk_mul_f32 v[34:35], v[24:25], v[32:33]
	v_pk_fma_f32 v[24:25], v[24:25], v[32:33], v[32:33] neg_lo:[1,0,0] neg_hi:[1,0,0]
	s_nop 0
	v_cndmask_b32_e32 v33, v25, v35, vcc
	v_cndmask_b32_e64 v32, v24, v34, s[40:41]
	v_pk_mul_f32 v[24:25], v[32:33], v[32:33]
	s_nop 0
	v_add_f32_e32 v24, v24, v37
	v_add_f32_e32 v24, v25, v24
	ds_bpermute_b32 v25, v85, v24
	s_waitcnt lgkmcnt(0)
; __device__ __forceinline__ unsigned cvt_pk_bf16(float lo, float hi) { unsigned r; asm volatile("v_cvt_pk_bf16_f32 %0, %1, %2" : "=v"(r) : "v"(lo), "v"(hi)); return r; }
; __device__ __forceinline__ float bflo(unsigned w) { return __uint_as_float(w << 16); }
; __device__ __forceinline__ float bfhi(unsigned w) { return __uint_as_float(w & 0xffff0000u); }
; #define SGU_LOAD(ch) do { _Pragma("unroll") for (int i = 0; i < 4; ++i) pv[i] = *(const u32x4*)(Z + (size_t)((ch) * 128 + lrow + 32 * i) * ZW + ZSV + g * 128 + cs); } while (0)
; PHASE_FN void sgu_block(const Params& p, unsigned char* lds, int l, int g, int ch0, int nch) {
;     ...
;         for (int i = 0; i < 4; ++i) { const u32x4 w = pv[i];
;             float v[8];
;             { const f32x2 a = gelu_pk((f32x2){bflo(w.x), bfhi(w.x)}), b2 = gelu_pk((f32x2){bflo(w.y), bfhi(w.y)}), c = gelu_pk((f32x2){bflo(w.z), bfhi(w.z)}), d = gelu_pk((f32x2){bflo(w.w), bfhi(w.w)});
;               v[0] = a.x; v[1] = a.y; v[2] = b2.x; v[3] = b2.y; v[4] = c.x; v[5] = c.y; v[6] = d.x; v[7] = d.y; }
;             float ss = 0.f;
; #pragma unroll
;             for (int k = 0; k < 8; ++k) ss += v[k] * v[k];
;             ss += __shfl_xor(ss, 1); ss += __shfl_xor(ss, 2); ss += __shfl_xor(ss, 4); ss += __shfl_xor(ss, 8);
;             const float rs = rsqrtf(ss * (1.0f / 128.0f) + EPS);
;             u32x4 o; o.x = cvt_pk_bf16(v[0] * rs * g0[0], v[1] * rs * g0[1]); o.y = cvt_pk_bf16(v[2] * rs * g0[2], v[3] * rs * g0[3]);
;             o.z = cvt_pk_bf16(v[4] * rs * g1[0], v[5] * rs * g1[1]); o.w = cvt_pk_bf16(v[6] * rs * g1[2], v[7] * rs * g1[3]);
;             *(u32x4*)(vt + (lrow + 32 * i) * SP + cs) = o; }
;         if (ch + 1 < ch0 + nch) SGU_LOAD(ch + 1);
	v_add_f32_e32 v24, v24, v25
	ds_bpermute_b32 v25, v86, v24
	s_waitcnt lgkmcnt(0)
	v_add_f32_e32 v24, v24, v25
	ds_bpermute_b32 v25, v87, v24
	s_waitcnt lgkmcnt(0)
	v_add_f32_e32 v24, v24, v25
	ds_bpermute_b32 v25, v88, v24
	s_waitcnt lgkmcnt(0)
	v_add_f32_e32 v24, v24, v25
	v_fmamk_f32 v24, v24, 0x3c000000, v208
	v_cmp_gt_f32_e32 vcc, s75, v24
	v_mul_f32_e32 v25, 0x4b800000, v24
	s_nop 0
	v_cndmask_b32_e32 v24, v24, v25, vcc
	v_rsq_f32_e32 v24, v24
	s_nop 0
	v_mul_f32_e32 v25, 0x45800000, v24
	v_cndmask_b32_e32 v34, v24, v25, vcc
	v_mul_f32_e32 v24, v29, v34
	v_mul_f32_e32 v25, v36, v34
	v_mul_f32_e32 v24, v0, v24
	v_mul_f32_e32 v25, v1, v25
	v_cvt_pk_bf16_f32 v24, v24, v25
	v_mul_f32_e32 v25, v26, v34
	v_mul_f32_e32 v26, v27, v34
	v_mul_f32_e32 v25, v2, v25
	v_mul_f32_e32 v26, v3, v26
	v_cvt_pk_bf16_f32 v25, v25, v26
	v_mul_f32_e32 v26, v30, v34
	v_mul_f32_e32 v27, v31, v34
	v_mul_f32_e32 v26, v4, v26
	v_mul_f32_e32 v27, v5, v27
	v_cvt_pk_bf16_f32 v26, v26, v27
	v_mul_f32_e32 v27, v32, v34
	v_mul_f32_e32 v27, v6, v27
	v_mul_f32_e32 v29, v33, v34
	v_mul_f32_e32 v29, v7, v29
	v_cvt_pk_bf16_f32 v27, v27, v29
	ds_write_b128 v28, v[24:27] offset:26112
	s_cbranch_scc1 .LBB0_253
	v_add_u32_e32 v20, s12, v90
	v_add_u32_e32 v8, 0xffff0080, v20
	v_mov_b64_e32 v[16:17], s[60:61]
	v_mad_i64_i32 v[8:9], s[14:15], v8, s1, v[16:17]
	v_lshl_add_u64 v[8:9], v[8:9], 0, s[76:77]
	v_add_u32_e32 v10, 0xffff00a0, v20
	v_lshl_add_u64 v[8:9], v[8:9], 0, v[152:153]
	v_mad_i64_i32 v[10:11], s[14:15], v10, s1, v[16:17]
	v_add_co_u32_e32 v8, vcc, 0x1000, v8
	v_lshl_add_u64 v[10:11], v[10:11], 0, s[76:77]
	v_add_u32_e32 v18, 0xffff00c0, v20
	v_addc_co_u32_e32 v9, vcc, 0, v9, vcc
	v_lshl_add_u64 v[10:11], v[10:11], 0, v[152:153]
	v_mad_i64_i32 v[18:19], s[14:15], v18, s1, v[16:17]
	v_add_co_u32_e32 v12, vcc, 0x1000, v10
	v_lshl_add_u64 v[18:19], v[18:19], 0, s[76:77]
	v_add_u32_e32 v20, 0xffff00e0, v20
	v_addc_co_u32_e32 v13, vcc, 0, v11, vcc
	v_lshl_add_u64 v[18:19], v[18:19], 0, v[152:153]
	v_mad_i64_i32 v[16:17], s[14:15], v20, s1, v[16:17]
	v_add_co_u32_e32 v18, vcc, 0x1000, v18
	v_lshl_add_u64 v[16:17], v[16:17], 0, s[76:77]
	s_nop 0
	v_addc_co_u32_e32 v19, vcc, 0, v19, vcc
	v_lshl_add_u64 v[16:17], v[16:17], 0, v[152:153]
	v_add_co_u32_e32 v20, vcc, 0x1000, v16
	global_load_dwordx4 v[8:11], v[8:9], off offset:512
	s_nop 0
	global_load_dwordx4 v[12:15], v[12:13], off offset:512
	v_addc_co_u32_e32 v21, vcc, 0, v17, vcc
	global_load_dwordx4 v[16:19], v[18:19], off offset:512
	s_nop 0
	global_load_dwordx4 v[20:23], v[20:21], off offset:512
	s_branch .LBB0_253

; __device__ __forceinline__ void gla_mma(const Params& p, unsigned char* lds, int l, int item, int tid) {
;     ...
;     for (int s = -1; s < 64; ++s) {
;         const int tok0 = b * SEQ + CHUNK(s < 0 ? 0 : s) * 64;
;     ...
;         if (s == 32) __syncthreads();
;         f32x4 accO[2][4]; u32x4 gw[4];
;         if (s >= 0) {
;             u32x4 ox[4];
;             bf16x8 vfrag[2][2];
; #pragma unroll
;             for (int vb = 0; vb < 2; ++vb)
; #pragma unroll
;                 for (int pp = 0; pp < 2; ++pp)
; #pragma unroll
;                     for (int i = 0; i < 8; ++i) { const int pos = 32 * pp + 4 * q4 + (i & 3) + ((i >> 2) << 4); vfrag[vb][pp][i] = (short)vraw[pos * VP + 32 * vq + 8 * (lr >> 2) + 4 * vb + (lr & 3)]; }
;             bf16x8 qf[4][2], kf[4][2];
; #pragma unroll
;             for (int cb = 0; cb < 4; ++cb) { qf[cb][0] = gla_tr_frag(qin, 8 * q4, 8 * q4 + 4, 16 * cb, lr); qf[cb][1] = gla_tr_frag(qin, 32 + 8 * q4, 36 + 8 * q4, 16 * cb, lr);
;                 kf[cb][0] = gla_tr_frag(kin, 8 * q4, 8 * q4 + 4, 16 * cb, lr); kf[cb][1] = gla_tr_frag(kin, 32 + 8 * q4, 36 + 8 * q4, 16 * cb, lr); }
;             bf16x8 P0[4], P1[2];
;             {
;                 f32x4 sc[4][4];
; #pragma unroll
;                 for (int cb = 0; cb < 4; ++cb)
; #pragma unroll
;                     for (int jb = 0; jb < 4; ++jb) {
;                         if (jb > cb) { sc[jb][cb] = (f32x4){0.f, 0.f, 0.f, 0.f}; continue; }
;                         f32x4 a = (f32x4){0.f, 0.f, 0.f, 0.f};
;                         a = __builtin_amdgcn_mfma_f32_16x16x32_bf16(kf[jb][0], qf[cb][0], a, 0, 0, 0);
;                         sc[jb][cb] = a;
;                     }
; #pragma unroll
;                 for (int cb = 0; cb < 4; ++cb)
; #pragma unroll
;                     for (int jb = 0; jb <= cb; ++jb) sc[jb][cb] = __builtin_amdgcn_mfma_f32_16x16x32_bf16(kf[jb][1], qf[cb][1], sc[jb][cb], 0, 0, 0);
;             __builtin_amdgcn_sched_barrier(0);
;             if (s >= 32) {
; #pragma unroll
;                 for (int cb = 0; cb < 4; ++cb) { const size_t tk = (size_t)TOK(16 * cb + lr); ox[cb] = *(const u32x4*)(OX + tk * 512 + ocol); gw[cb] = *(const u32x4*)(Z + tk * ZW + ZG + ocol); }
;             }
.LBB0_264:
	s_add_i32 s7, s5, 31
	s_max_i32 s6, s7, 0
	v_readlane_b32 s8, v247, 42
	s_sub_i32 s10, 63, s6
	v_readlane_b32 s9, v247, 43
	s_and_b64 s[8:9], s[8:9], exec
	s_cselect_b32 s6, s6, s10
	s_lshl_b32 s6, s6, 6
	v_readlane_b32 s8, v247, 57
	s_add_i32 s6, s6, s8
	s_cmp_lt_i32 s7, 0
	v_or_b32_e32 v140, s6, v150
	s_cbranch_scc1 .LBB0_279
	ds_read_b64_tr_b16 v[72:73], v145 offset:9216
	ds_read_b64_tr_b16 v[74:75], v145 offset:9792
	ds_read_b64_tr_b16 v[76:77], v145
	ds_read_b64_tr_b16 v[80:81], v145 offset:32
	ds_read_b64_tr_b16 v[84:85], v145 offset:64
	ds_read_b64_tr_b16 v[88:89], v145 offset:96
	ds_read_b64_tr_b16 v[78:79], v145 offset:576
	ds_read_b64_tr_b16 v[82:83], v145 offset:608
	ds_read_b64_tr_b16 v[86:87], v145 offset:640
	ds_read_b64_tr_b16 v[90:91], v145 offset:672
	ds_read_b64_tr_b16 v[92:93], v145 offset:9248
	ds_read_b64_tr_b16 v[96:97], v145 offset:9280
	ds_read_b64_tr_b16 v[100:101], v145 offset:9312
	ds_read_b64_tr_b16 v[94:95], v145 offset:9824
	ds_read_b64_tr_b16 v[98:99], v145 offset:9856
	ds_read_b64_tr_b16 v[102:103], v145 offset:9888
	s_waitcnt lgkmcnt(9)
	v_mfma_f32_16x16x32_bf16 v[76:79], v[72:75], v[76:79], 0
	ds_read_b64_tr_b16 v[126:127], v145 offset:13824
	ds_read_b64_tr_b16 v[128:129], v145 offset:14400
	s_waitcnt lgkmcnt(10)
	v_mfma_f32_16x16x32_bf16 v[104:107], v[72:75], v[80:83], 0
	s_waitcnt lgkmcnt(9)
	v_mfma_f32_16x16x32_bf16 v[112:115], v[72:75], v[84:87], 0
	s_waitcnt lgkmcnt(8)
	v_mfma_f32_16x16x32_bf16 v[130:133], v[72:75], v[88:91], 0
	ds_read_b64_tr_b16 v[72:73], v145 offset:4608
	ds_read_b64_tr_b16 v[120:121], v145 offset:4640
	ds_read_b64_tr_b16 v[174:175], v145 offset:4672
	ds_read_b64_tr_b16 v[182:183], v145 offset:4704
	ds_read_b64_tr_b16 v[74:75], v145 offset:5184
	ds_read_b64_tr_b16 v[122:123], v145 offset:5216
	ds_read_b64_tr_b16 v[176:177], v145 offset:5248
	ds_read_b64_tr_b16 v[184:185], v145 offset:5280
	ds_read_b64_tr_b16 v[190:191], v145 offset:13856
	ds_read_b64_tr_b16 v[194:195], v145 offset:13888
	ds_read_b64_tr_b16 v[198:199], v145 offset:13920
	s_waitcnt lgkmcnt(14)
	v_mfma_f32_16x16x32_bf16 v[80:83], v[92:95], v[80:83], 0
	ds_read_b64_tr_b16 v[192:193], v145 offset:14432
	ds_read_b64_tr_b16 v[196:197], v145 offset:14464
	ds_read_b64_tr_b16 v[200:201], v145 offset:14496
	v_mfma_f32_16x16x32_bf16 v[116:119], v[92:95], v[84:87], 0
	v_mfma_f32_16x16x32_bf16 v[84:87], v[96:99], v[84:87], 0
	v_mfma_f32_16x16x32_bf16 v[178:181], v[92:95], v[88:91], 0
	v_mfma_f32_16x16x32_bf16 v[186:189], v[96:99], v[88:91], 0
	s_waitcnt lgkmcnt(14)
	v_mfma_f32_16x16x32_bf16 v[100:103], v[100:103], v[88:91], 0
	s_waitcnt lgkmcnt(9)
	v_mfma_f32_16x16x32_bf16 v[108:111], v[126:129], v[72:75], v[76:79]
	s_waitcnt lgkmcnt(8)
	v_mfma_f32_16x16x32_bf16 v[96:99], v[126:129], v[120:123], v[104:107]
	s_waitcnt lgkmcnt(2)
	v_mfma_f32_16x16x32_bf16 v[104:107], v[190:193], v[120:123], v[80:83]
	v_mfma_f32_16x16x32_bf16 v[92:95], v[126:129], v[174:177], v[112:115]
	v_mfma_f32_16x16x32_bf16 v[80:83], v[190:193], v[174:177], v[116:119]
	s_nop 2
	ds_read_u16 v119, v167 offset:56576
	ds_read_u16 v116, v167 offset:56584
	ds_read_u16 v120, v168 offset:56576
	ds_read_u16 v117, v168 offset:56584
	ds_read_u16 v121, v169 offset:56576
	ds_read_u16 v118, v169 offset:56584
	ds_read_u16 v122, v170 offset:56576
	ds_read_u16 v124, v170 offset:56584
	s_waitcnt lgkmcnt(9)
	v_mfma_f32_16x16x32_bf16 v[72:75], v[194:197], v[174:177], v[84:87]
	v_mfma_f32_16x16x32_bf16 v[76:79], v[126:129], v[182:185], v[130:133]
	ds_read_u16 v114, v163 offset:56576
	ds_read_u16 v112, v163 offset:56584
	s_nop 0
	ds_read_u16 v131, v163 offset:56840
	ds_read_u16 v133, v163 offset:57104
	ds_read_u16 v135, v163 offset:57368
	ds_read_u16 v113, v163 offset:57376
	ds_read_u16 v115, v163 offset:57112
	ds_read_u16 v129, v163 offset:56848
	v_mfma_f32_16x16x32_bf16 v[88:91], v[190:193], v[182:185], v[178:181]
	ds_read_u16 v176, v163 offset:60800
	s_nop 1
	ds_read_u16 v178, v163 offset:61064
	ds_read_u16 v179, v163 offset:61328
	ds_read_u16 v180, v163 offset:61592
	ds_read_u16 v173, v163 offset:61600
	ds_read_u16 v175, v163 offset:61336
	ds_read_u16 v174, v163 offset:61072
	ds_read_u16 v177, v163 offset:60808
	ds_read_u16 v123, v164 offset:56576
	ds_read_u16 v125, v164 offset:56584
	ds_read_u16 v130, v163 offset:65288
	ds_read_u16 v132, v165 offset:56576
	ds_read_u16 v126, v165 offset:56584
	ds_read_u16 v134, v166 offset:56576
	ds_read_u16 v128, v166 offset:56584
	ds_read_u16 v127, v163 offset:65296
	v_mfma_f32_16x16x32_bf16 v[84:87], v[194:197], v[182:185], v[186:189]
	s_waitcnt lgkmcnt(14)
	v_mfma_f32_16x16x32_bf16 v[100:103], v[198:201], v[182:185], v[100:103]
	s_cmp_lt_u32 s7, 32
	v_ashrrev_i32_e32 v141, 31, v140
	s_cbranch_scc1 .LBB0_267
	v_or_b32_e32 v8, s6, v149
	v_ashrrev_i32_e32 v9, 31, v8
	v_mov_b64_e32 v[48:49], s[86:87]
	v_lshlrev_b64 v[10:11], 10, v[8:9]
	v_mad_i64_i32 v[8:9], s[8:9], v8, s1, v[48:49]
	v_lshl_add_u64 v[8:9], v[8:9], 0, v[152:153]
	v_add_co_u32_e32 v12, vcc, 0xec00000, v8
	v_mad_i64_i32 v[18:19], s[8:9], v140, s1, v[48:49]
	v_or_b32_e32 v32, s6, v151
	v_addc_co_u32_e32 v13, vcc, 0, v9, vcc
	v_lshl_add_u64 v[18:19], v[18:19], 0, v[152:153]
	v_ashrrev_i32_e32 v33, 31, v32
	v_add_co_u32_e32 v20, vcc, 0xec00000, v18
	v_lshlrev_b64 v[34:35], 10, v[32:33]
	v_mad_i64_i32 v[32:33], s[8:9], v32, s1, v[48:49]
	v_addc_co_u32_e32 v21, vcc, 0, v19, vcc
	v_lshl_add_u64 v[32:33], v[32:33], 0, v[152:153]
	v_or_b32_e32 v50, s6, v162
	v_add_co_u32_e32 v36, vcc, 0xec00000, v32
	v_mad_i64_i32 v[48:49], s[8:9], v50, s1, v[48:49]
	s_nop 0
	v_addc_co_u32_e32 v37, vcc, 0, v33, vcc
	v_ashrrev_i32_e32 v51, 31, v50
	v_lshl_add_u64 v[48:49], v[48:49], 0, v[152:153]
	v_lshlrev_b64 v[16:17], 10, v[140:141]
	v_lshlrev_b64 v[56:57], 10, v[50:51]
	v_add_co_u32_e32 v58, vcc, 0xec00000, v48
	v_lshl_add_u64 v[10:11], v[136:137], 0, v[10:11]
	v_lshl_add_u64 v[16:17], v[136:137], 0, v[16:17]
	v_lshl_add_u64 v[34:35], v[136:137], 0, v[34:35]
	v_lshl_add_u64 v[56:57], v[136:137], 0, v[56:57]
	v_addc_co_u32_e32 v59, vcc, 0, v49, vcc
	global_load_dwordx4 v[8:11], v[10:11], off
	s_nop 0
	global_load_dwordx4 v[12:15], v[12:13], off offset:2048
	s_nop 0
	global_load_dwordx4 v[16:19], v[16:17], off
	s_nop 0
	global_load_dwordx4 v[20:23], v[20:21], off offset:2048
	s_nop 0
	global_load_dwordx4 v[32:35], v[34:35], off
	s_nop 0
	global_load_dwordx4 v[36:39], v[36:37], off offset:2048
	s_nop 0
	global_load_dwordx4 v[48:51], v[56:57], off
	s_nop 0
	global_load_dwordx4 v[56:59], v[58:59], off offset:2048
